# P5 slack filling: the 248 workgroups without the extra sample P5b item convert 1984 FFN2 gate/up weight items after P5 (moved out of P0)
# speedup vs baseline: 1.0066x; 1.0066x over previous
; __global__ void __launch_bounds__(NTHREADS, 2) fwd_kernel(Params P) {
;     ...
;         for (int it = gw; it < IT_TOTAL; it += NGW) {
;             int r = it; const float* W; bf16_t* WT; int N, ldk, mode = 0; const float* fg = nullptr; const float* fb = nullptr; float* cs = nullptr;
;             if (r < IT_GU) { W = P.in[I_WIN]; WT = WIN; N = NZ; ldk = D; fg = P.in[I_LN1G]; fb = P.in[I_LN1B]; cs = CSUM; }
;             else if ((r -= IT_GU) < IT_SQ) { W = P.in[I_WKV]; WT = WKV; N = D; ldk = D; }
;             else if ((r -= IT_SQ) < 3 * IT_BR) { const int k = r / IT_BR; r -= k * IT_BR; W = P.in[I_WBR] + (size_t)k * BW * D; WT = WBR + (size_t)k * D * BW; N = D; ldk = BW; }
;             else if ((r -= 3 * IT_BR) < IT_SQ) { W = P.in[I_WOUT]; WT = WOUT; N = D; ldk = D; }
;             else if ((r -= IT_SQ) < IT_GU) { W = P.in[I_GU2]; WT = WGU2; N = NZ; ldk = D; mode = 1; fg = P.in[I_LN2G]; fb = P.in[I_LN2B]; cs = CSUM + 2 * NZ; }
;             else if ((r -= IT_GU) < IT_DN) { W = P.in[I_DN2]; WT = WD2; N = D; ldk = FF; }
;             else if ((r -= IT_DN) < 16 * IT_LR) { const int m = r / IT_LR; r -= m * IT_LR; const int k = m >> 1, x = m & 1;
;                 W = (x ? P.in[I_LWX] : P.in[I_LWA]) + (size_t)k * 128 * 128; WT = WLRU + (size_t)k * 256 * 128 + x * 128 * 128; N = 128; ldk = 128; }
;             else if ((r -= 16 * IT_LR) < IT_DN) { W = P.in[I_DN1]; WT = WD1; N = D; ldk = FF; }
;             else { r -= IT_DN; W = P.in[I_GU1]; WT = WGU1; N = NZ; ldk = D; mode = 1; }
;             const int nblk = N / 32, kb = r / nblk, nb = r % nblk, n0 = 32 * nb;
;             int dr = n0;
;             if (mode == 1) dr = (n0 < FF) ? (n0 / 128) * 256 + (n0 % 128) : ((n0 - FF) / 128) * 256 + 128 + ((n0 - FF) % 128);
;             transpose_item(W, N, WT, ldk, 64 * kb, n0, dr, scr, lane, fg, fb, cs);
;         }
.Lcv_exit:
	s_cmp_lg_u32 s100, 0
	s_cbranch_scc1 .Lcv_d1
	s_mov_b32 s100, 1
	s_mov_b32 s98, 0x73ff
	v_readlane_b32 s99, v255, 13
	s_lshl_b32 s101, s34, 3
	s_nop 3
	s_add_i32 s99, s99, s101
	s_add_i32 s99, s99, 0x400
	s_and_b32 s99, s99, 0x7ff
	s_add_i32 s30, s99, 0x5ec0
	s_branch .Lcv_entry

; __global__ void __launch_bounds__(NTHREADS, 2) fwd_kernel(Params P) {
;     ...
;         for (int it = gw; it < IT_TOTAL; it += NGW) {
;             int r = it; const float* W; bf16_t* WT; int N, ldk, mode = 0; const float* fg = nullptr; const float* fb = nullptr; float* cs = nullptr;
;             if (r < IT_GU) { W = P.in[I_WIN]; WT = WIN; N = NZ; ldk = D; fg = P.in[I_LN1G]; fb = P.in[I_LN1B]; cs = CSUM; }
;             else if ((r -= IT_GU) < IT_SQ) { W = P.in[I_WKV]; WT = WKV; N = D; ldk = D; }
;             else if ((r -= IT_SQ) < 3 * IT_BR) { const int k = r / IT_BR; r -= k * IT_BR; W = P.in[I_WBR] + (size_t)k * BW * D; WT = WBR + (size_t)k * D * BW; N = D; ldk = BW; }
;             else if ((r -= 3 * IT_BR) < IT_SQ) { W = P.in[I_WOUT]; WT = WOUT; N = D; ldk = D; }
;             else if ((r -= IT_SQ) < IT_GU) { W = P.in[I_GU2]; WT = WGU2; N = NZ; ldk = D; mode = 1; fg = P.in[I_LN2G]; fb = P.in[I_LN2B]; cs = CSUM + 2 * NZ; }
;             else if ((r -= IT_GU) < IT_DN) { W = P.in[I_DN2]; WT = WD2; N = D; ldk = FF; }
;             else if ((r -= IT_DN) < 16 * IT_LR) { const int m = r / IT_LR; r -= m * IT_LR; const int k = m >> 1, x = m & 1;
;                 W = (x ? P.in[I_LWX] : P.in[I_LWA]) + (size_t)k * 128 * 128; WT = WLRU + (size_t)k * 256 * 128 + x * 128 * 128; N = 128; ldk = 128; }
;             else if ((r -= 16 * IT_LR) < IT_DN) { W = P.in[I_DN1]; WT = WD1; N = D; ldk = FF; }
;             else { r -= IT_DN; W = P.in[I_GU1]; WT = WGU1; N = NZ; ldk = D; mode = 1; }
;             const int nblk = N / 32, kb = r / nblk, nb = r % nblk, n0 = 32 * nb;
;             int dr = n0;
;             if (mode == 1) dr = (n0 < FF) ? (n0 / 128) * 256 + (n0 % 128) : ((n0 - FF) / 128) * 256 + 128 + ((n0 - FF) % 128);
;             transpose_item(W, N, WT, ldk, 64 * kb, n0, dr, scr, lane, fg, fb, cs);
;         }
.Lcv_d3:
	s_cmp_lg_u32 s100, 3
	s_cbranch_scc0 .Lcv_ret_p1
	s_cmp_lg_u32 s100, 4
	s_cbranch_scc0 .Lcv_ret_p4
	s_cmp_lg_u32 s100, 5
	s_cbranch_scc1 .Lcv_n2
	s_branch .Lcv_hop_ret_p5

; __device__ __forceinline__ void xcd_barrier(const XcdBarrier& b) {
;     asm volatile("s_waitcnt vmcnt(0)" ::: "memory");
;     __syncthreads();
; __global__ void __launch_bounds__(NTHREADS, 2) fwd_kernel(Params P) {
;     ...
;         for (int it = gw; it < IT_TOTAL; it += NGW) {
;             int r = it; const float* W; bf16_t* WT; int N, ldk, mode = 0; const float* fg = nullptr; const float* fb = nullptr; float* cs = nullptr;
;             if (r < IT_GU) { W = P.in[I_WIN]; WT = WIN; N = NZ; ldk = D; fg = P.in[I_LN1G]; fb = P.in[I_LN1B]; cs = CSUM; }
;             else if ((r -= IT_GU) < IT_SQ) { W = P.in[I_WKV]; WT = WKV; N = D; ldk = D; }
;             else if ((r -= IT_SQ) < 3 * IT_BR) { const int k = r / IT_BR; r -= k * IT_BR; W = P.in[I_WBR] + (size_t)k * BW * D; WT = WBR + (size_t)k * D * BW; N = D; ldk = BW; }
;             else if ((r -= 3 * IT_BR) < IT_SQ) { W = P.in[I_WOUT]; WT = WOUT; N = D; ldk = D; }
;             else if ((r -= IT_SQ) < IT_GU) { W = P.in[I_GU2]; WT = WGU2; N = NZ; ldk = D; mode = 1; fg = P.in[I_LN2G]; fb = P.in[I_LN2B]; cs = CSUM + 2 * NZ; }
;             else if ((r -= IT_GU) < IT_DN) { W = P.in[I_DN2]; WT = WD2; N = D; ldk = FF; }
;             else if ((r -= IT_DN) < 16 * IT_LR) { const int m = r / IT_LR; r -= m * IT_LR; const int k = m >> 1, x = m & 1;
;                 W = (x ? P.in[I_LWX] : P.in[I_LWA]) + (size_t)k * 128 * 128; WT = WLRU + (size_t)k * 256 * 128 + x * 128 * 128; N = 128; ldk = 128; }
;             else if ((r -= 16 * IT_LR) < IT_DN) { W = P.in[I_DN1]; WT = WD1; N = D; ldk = FF; }
;             else { r -= IT_DN; W = P.in[I_GU1]; WT = WGU1; N = NZ; ldk = D; mode = 1; }
;             const int nblk = N / 32, kb = r / nblk, nb = r % nblk, n0 = 32 * nb;
;             int dr = n0;
;             if (mode == 1) dr = (n0 < FF) ? (n0 / 128) * 256 + (n0 % 128) : ((n0 - FF) / 128) * 256 + 128 + ((n0 - FF) % 128);
;             transpose_item(W, N, WT, ldk, 64 * kb, n0, dr, scr, lane, fg, fb, cs);
;         }
.LBB0_641:
	s_waitcnt vmcnt(0)
	s_barrier
	s_cmp_lt_u32 s34, 8
	s_cbranch_scc1 .Lcv_skip_p5
	v_writelane_b32 v252, s0, 0
	v_writelane_b32 v252, s1, 1
	v_writelane_b32 v252, s2, 2
	v_writelane_b32 v252, s3, 3
	v_writelane_b32 v252, s4, 4
	v_writelane_b32 v252, s5, 5
	v_writelane_b32 v252, s6, 6
	v_writelane_b32 v252, s7, 7
	v_writelane_b32 v252, s8, 8
	v_writelane_b32 v252, s9, 9
	v_writelane_b32 v252, s10, 10
	v_writelane_b32 v252, s11, 11
	v_writelane_b32 v252, s12, 12
	v_writelane_b32 v252, s13, 13
	v_writelane_b32 v252, s14, 14
	v_writelane_b32 v252, s15, 15
	v_writelane_b32 v252, s16, 16
	v_writelane_b32 v252, s17, 17
	v_writelane_b32 v252, s18, 18
	v_writelane_b32 v252, s19, 19
	v_writelane_b32 v252, s20, 20
	v_writelane_b32 v252, s21, 21
	v_writelane_b32 v252, s22, 22
	v_writelane_b32 v252, s23, 23
	v_writelane_b32 v252, s24, 24
	v_writelane_b32 v252, s25, 25
	v_writelane_b32 v252, s26, 26
	v_writelane_b32 v252, s27, 27
	v_writelane_b32 v252, s28, 28
	v_writelane_b32 v252, s29, 29
	v_writelane_b32 v252, s30, 30
	v_writelane_b32 v252, s31, 31
	v_writelane_b32 v252, s32, 32
	v_writelane_b32 v252, s33, 33
	v_writelane_b32 v252, s34, 34
	v_writelane_b32 v252, s35, 35
	v_writelane_b32 v252, s36, 36
	v_writelane_b32 v252, s37, 37
	v_writelane_b32 v252, s38, 38
	v_writelane_b32 v252, s39, 39
	v_writelane_b32 v252, s40, 40
	v_writelane_b32 v252, s41, 41
	v_writelane_b32 v252, s42, 42
	v_writelane_b32 v252, s43, 43
	v_writelane_b32 v252, s44, 44
	v_writelane_b32 v252, s45, 45
	v_writelane_b32 v252, s46, 46
	v_writelane_b32 v252, s47, 47
	v_writelane_b32 v252, s48, 48
	v_writelane_b32 v252, s49, 49
	v_writelane_b32 v252, s50, 50
	v_writelane_b32 v252, s51, 51
	v_writelane_b32 v252, s52, 52
	v_writelane_b32 v252, s53, 53
	v_writelane_b32 v252, s54, 54
	v_writelane_b32 v252, s55, 55
	v_writelane_b32 v252, s56, 56
	v_writelane_b32 v252, s57, 57
	v_writelane_b32 v252, s58, 58
	v_writelane_b32 v252, s59, 59
	v_writelane_b32 v252, s60, 60
	v_writelane_b32 v252, s61, 61
	v_writelane_b32 v252, s62, 62
	v_writelane_b32 v252, s63, 63
	v_writelane_b32 v253, s64, 0
	v_writelane_b32 v253, s65, 1
	v_writelane_b32 v253, s66, 2
	v_writelane_b32 v253, s67, 3
	v_writelane_b32 v253, s68, 4
	v_writelane_b32 v253, s69, 5
	v_writelane_b32 v253, s70, 6
	v_writelane_b32 v253, s71, 7
	v_writelane_b32 v253, s72, 8
	v_writelane_b32 v253, s73, 9
	v_writelane_b32 v253, s74, 10
	v_writelane_b32 v253, s75, 11
	v_writelane_b32 v253, s76, 12
	v_writelane_b32 v253, s77, 13
	v_writelane_b32 v253, s78, 14
	v_writelane_b32 v253, s79, 15
	v_writelane_b32 v253, s80, 16
	v_writelane_b32 v253, s81, 17
	v_writelane_b32 v253, s82, 18
	v_writelane_b32 v253, s83, 19
	v_writelane_b32 v253, s84, 20
	v_writelane_b32 v253, s85, 21
	v_writelane_b32 v253, s86, 22
	v_writelane_b32 v253, s87, 23
	v_writelane_b32 v253, s88, 24
	v_writelane_b32 v253, s89, 25
	v_writelane_b32 v253, s90, 26
	v_writelane_b32 v253, s91, 27
	v_writelane_b32 v253, s92, 28
	v_writelane_b32 v253, s93, 29
	v_writelane_b32 v253, s94, 30
	v_writelane_b32 v253, s95, 31
	v_writelane_b32 v253, s96, 32
	v_writelane_b32 v253, s97, 33
	s_mov_b32 s100, 5
	s_mov_b32 s98, 0x5ebf
	v_and_b32_e32 v237, 63, v178
	v_readlane_b32 s99, v255, 13
	v_readfirstlane_b32 s37, v178
	s_nop 4
	s_sub_i32 s101, s34, 8
	s_lshl_b32 s101, s101, 3
	s_add_i32 s99, s99, s101
	s_add_i32 s30, s99, 0x5700
	s_movk_i32 s86, 1984
	s_branch .Lcv_hop_entry

; __device__ __forceinline__ unsigned xb_ld(unsigned* p)              { return __hip_atomic_load(p, __ATOMIC_RELAXED, __HIP_MEMORY_SCOPE_AGENT); }
; __device__ __forceinline__ void xcd_barrier_complete(unsigned* bar, unsigned x, unsigned& nloc, unsigned& nx) {
;     const unsigned G = gridDim.x * gridDim.y * gridDim.z;
;     unsigned sum, cnt, mine, sp = 0u;
;     for (;;) {
;         sum = 0u; cnt = 0u; mine = 0u;
; #pragma unroll
;         for (unsigned j = 0; j < 16; ++j) { const unsigned c = xb_ld(&bar[XB_XCNT(j)]); sum += c; cnt += (c > 0u) ? 1u : 0u; mine = (j == x) ? c : mine; }
; __device__ __forceinline__ void xcd_barrier(const XcdBarrier& b) {
;     ...
;     if (threadIdx.x == 0) {
;         unsigned* bar = b.bar;
;         __builtin_amdgcn_s_waitcnt(0);
;         unsigned nloc = b.st[0], nx = b.st[1];
;         if (nloc == 0u) { xcd_barrier_complete(bar, b.x, nloc, nx); b.st[0] = nloc; b.st[1] = nx; }
.Lcv_skip_p5:
	s_mov_b64 s[0:1], exec
	v_readlane_b32 s2, v254, 9
	v_readlane_b32 s3, v254, 10
	v_readlane_b32 s50, v255, 27
	s_and_b64 s[2:3], s[0:1], s[2:3]
	v_readlane_b32 s70, v255, 16
	v_readlane_b32 s51, v255, 28
	v_readlane_b32 s71, v255, 17
	s_mov_b64 exec, s[2:3]
	s_cbranch_execz .LBB0_693
	s_add_i32 s2, 0, 0x26fc0
	v_mov_b32_e32 v0, s2
	s_waitcnt vmcnt(0) expcnt(0) lgkmcnt(0)
	ds_read_b32 v2, v0
	s_add_i32 s2, 0, 0x26fc4
	v_mov_b32_e32 v0, s2
	ds_read_b32 v0, v0
	s_waitcnt lgkmcnt(1)
	v_cmp_ne_u32_e32 vcc, 0, v2
	s_cbranch_vccnz .LBB0_657
	s_add_u32 s4, s92, 0x2b1a0200
	s_addc_u32 s5, s93, 0
	s_add_u32 s6, s92, 0x2b1a0400
	s_addc_u32 s7, s93, 0
	s_add_u32 s8, s92, 0x2b1a0500
	s_addc_u32 s9, s93, 0
	s_add_u32 s10, s92, 0x2b1a0600
	s_addc_u32 s11, s93, 0
	s_add_u32 s12, s92, 0x2b1a0700
	s_addc_u32 s13, s93, 0
	s_add_u32 s14, s92, 0x2b1a0800
	s_addc_u32 s15, s93, 0
	s_add_u32 s16, s92, 0x2b1a0900
	s_addc_u32 s17, s93, 0
	s_add_u32 s18, s92, 0x2b1a0a00
	s_addc_u32 s19, s93, 0
	s_add_u32 s20, s92, 0x2b1a0b00
	s_addc_u32 s21, s93, 0
	s_add_u32 s22, s92, 0x2b1a0c00
	s_addc_u32 s23, s93, 0
	s_add_u32 s24, s92, 0x2b1a0d00
	s_addc_u32 s25, s93, 0
	s_add_u32 s26, s92, 0x2b1a0e00
	s_addc_u32 s27, s93, 0
	s_add_u32 s28, s92, 0x2b1a0f00
	s_addc_u32 s29, s93, 0
	s_add_u32 s36, s92, 0x2b1a1000
	s_addc_u32 s37, s93, 0
	s_add_u32 s42, s92, 0x2b1a1100
	s_addc_u32 s43, s93, 0
	s_add_u32 s44, s92, 0x2b1a1200
	v_readlane_b32 s2, v254, 8
	s_addc_u32 s45, s93, 0
	s_mul_i32 s2, s95, s2
	s_add_u32 s46, s92, 0x2b1a1300
	s_mul_i32 s2, s2, s94
	s_addc_u32 s47, s93, 0
	s_mov_b32 s3, 1
	v_mov_b32_e32 v16, 0
	s_branch .LBB0_645

; __global__ void __launch_bounds__(NTHREADS, 2) fwd_kernel(Params P) {
;     ...
;         for (int it = gw; it < IT_TOTAL; it += NGW) {
;             int r = it; const float* W; bf16_t* WT; int N, ldk, mode = 0; const float* fg = nullptr; const float* fb = nullptr; float* cs = nullptr;
;             if (r < IT_GU) { W = P.in[I_WIN]; WT = WIN; N = NZ; ldk = D; fg = P.in[I_LN1G]; fb = P.in[I_LN1B]; cs = CSUM; }
;             else if ((r -= IT_GU) < IT_SQ) { W = P.in[I_WKV]; WT = WKV; N = D; ldk = D; }
;             else if ((r -= IT_SQ) < 3 * IT_BR) { const int k = r / IT_BR; r -= k * IT_BR; W = P.in[I_WBR] + (size_t)k * BW * D; WT = WBR + (size_t)k * D * BW; N = D; ldk = BW; }
;             else if ((r -= 3 * IT_BR) < IT_SQ) { W = P.in[I_WOUT]; WT = WOUT; N = D; ldk = D; }
;             else if ((r -= IT_SQ) < IT_GU) { W = P.in[I_GU2]; WT = WGU2; N = NZ; ldk = D; mode = 1; fg = P.in[I_LN2G]; fb = P.in[I_LN2B]; cs = CSUM + 2 * NZ; }
;             else if ((r -= IT_GU) < IT_DN) { W = P.in[I_DN2]; WT = WD2; N = D; ldk = FF; }
;             else if ((r -= IT_DN) < 16 * IT_LR) { const int m = r / IT_LR; r -= m * IT_LR; const int k = m >> 1, x = m & 1;
;                 W = (x ? P.in[I_LWX] : P.in[I_LWA]) + (size_t)k * 128 * 128; WT = WLRU + (size_t)k * 256 * 128 + x * 128 * 128; N = 128; ldk = 128; }
;             else if ((r -= 16 * IT_LR) < IT_DN) { W = P.in[I_DN1]; WT = WD1; N = D; ldk = FF; }
;             else { r -= IT_DN; W = P.in[I_GU1]; WT = WGU1; N = NZ; ldk = D; mode = 1; }
;             const int nblk = N / 32, kb = r / nblk, nb = r % nblk, n0 = 32 * nb;
;             int dr = n0;
;             if (mode == 1) dr = (n0 < FF) ? (n0 / 128) * 256 + (n0 % 128) : ((n0 - FF) / 128) * 256 + 128 + ((n0 - FF) % 128);
;             transpose_item(W, N, WT, ldk, 64 * kb, n0, dr, scr, lane, fg, fb, cs);
;         }
.LBB0_1044:
	s_cmp_lt_u32 s34, 172
	s_cbranch_scc1 .Lcv_skip_p10
	v_writelane_b32 v252, s0, 0
	v_writelane_b32 v252, s1, 1
	v_writelane_b32 v252, s2, 2
	v_writelane_b32 v252, s3, 3
	v_writelane_b32 v252, s4, 4
	v_writelane_b32 v252, s5, 5
	v_writelane_b32 v252, s6, 6
	v_writelane_b32 v252, s7, 7
	v_writelane_b32 v252, s8, 8
	v_writelane_b32 v252, s9, 9
	v_writelane_b32 v252, s10, 10
	v_writelane_b32 v252, s11, 11
	v_writelane_b32 v252, s12, 12
	v_writelane_b32 v252, s13, 13
	v_writelane_b32 v252, s14, 14
	v_writelane_b32 v252, s15, 15
	v_writelane_b32 v252, s16, 16
	v_writelane_b32 v252, s17, 17
	v_writelane_b32 v252, s18, 18
	v_writelane_b32 v252, s19, 19
	v_writelane_b32 v252, s20, 20
	v_writelane_b32 v252, s21, 21
	v_writelane_b32 v252, s22, 22
	v_writelane_b32 v252, s23, 23
	v_writelane_b32 v252, s24, 24
	v_writelane_b32 v252, s25, 25
	v_writelane_b32 v252, s26, 26
	v_writelane_b32 v252, s27, 27
	v_writelane_b32 v252, s28, 28
	v_writelane_b32 v252, s29, 29
	v_writelane_b32 v252, s30, 30
	v_writelane_b32 v252, s31, 31
	v_writelane_b32 v252, s32, 32
	v_writelane_b32 v252, s33, 33
	v_writelane_b32 v252, s34, 34
	v_writelane_b32 v252, s35, 35
	v_writelane_b32 v252, s36, 36
	v_writelane_b32 v252, s37, 37
	v_writelane_b32 v252, s38, 38
	v_writelane_b32 v252, s39, 39
	v_writelane_b32 v252, s40, 40
	v_writelane_b32 v252, s41, 41
	v_writelane_b32 v252, s42, 42
	v_writelane_b32 v252, s43, 43
	v_writelane_b32 v252, s44, 44
	v_writelane_b32 v252, s45, 45
	v_writelane_b32 v252, s46, 46
	v_writelane_b32 v252, s47, 47
	v_writelane_b32 v252, s48, 48
	v_writelane_b32 v252, s49, 49
	v_writelane_b32 v252, s50, 50
	v_writelane_b32 v252, s51, 51
	v_writelane_b32 v252, s52, 52
	v_writelane_b32 v252, s53, 53
	v_writelane_b32 v252, s54, 54
	v_writelane_b32 v252, s55, 55
	v_writelane_b32 v252, s56, 56
	v_writelane_b32 v252, s57, 57
	v_writelane_b32 v252, s58, 58
	v_writelane_b32 v252, s59, 59
	v_writelane_b32 v252, s60, 60
	v_writelane_b32 v252, s61, 61
	v_writelane_b32 v252, s62, 62
	v_writelane_b32 v252, s63, 63
	v_writelane_b32 v253, s64, 0
	v_writelane_b32 v253, s65, 1
	v_writelane_b32 v253, s66, 2
	v_writelane_b32 v253, s67, 3
	v_writelane_b32 v253, s68, 4
	v_writelane_b32 v253, s69, 5
	v_writelane_b32 v253, s70, 6
	v_writelane_b32 v253, s71, 7
	v_writelane_b32 v253, s72, 8
	v_writelane_b32 v253, s73, 9
	v_writelane_b32 v253, s74, 10
	v_writelane_b32 v253, s75, 11
	v_writelane_b32 v253, s76, 12
	v_writelane_b32 v253, s77, 13
	v_writelane_b32 v253, s78, 14
	v_writelane_b32 v253, s79, 15
	v_writelane_b32 v253, s80, 16
	v_writelane_b32 v253, s81, 17
	v_writelane_b32 v253, s82, 18
	v_writelane_b32 v253, s83, 19
	v_writelane_b32 v253, s84, 20
	v_writelane_b32 v253, s85, 21
	v_writelane_b32 v253, s86, 22
	v_writelane_b32 v253, s87, 23
	v_writelane_b32 v253, s88, 24
	v_writelane_b32 v253, s89, 25
	v_writelane_b32 v253, s90, 26
	v_writelane_b32 v253, s91, 27
	v_writelane_b32 v253, s92, 28
	v_writelane_b32 v253, s93, 29
	v_writelane_b32 v253, s94, 30
	v_writelane_b32 v253, s95, 31
	v_writelane_b32 v253, s96, 32
	v_writelane_b32 v253, s97, 33
	s_mov_b32 s100, 6
	s_mov_b32 s98, 0x89ff
	v_and_b32_e32 v237, 63, v178
	v_readlane_b32 s99, v255, 13
	v_readfirstlane_b32 s37, v178
	s_nop 4
	s_sub_i32 s101, s34, 172
	s_lshl_b32 s101, s101, 3
	s_add_i32 s99, s99, s101
	s_add_i32 s30, s99, 0x7400
	s_movk_i32 s86, 672
	s_branch .Lcv_hop_entry
